# P9 hidden-activation stores made streaming write-through (sc0 sc1 nt): P10 re-reads them while HBM is otherwise idle during its GEMM
# baseline (speedup 1.0000x reference)
.LBB0_1429:
	v_lshl_add_u32 v148, s2, 8, v152
	v_ashrrev_i32_e32 v149, 31, v148
	v_lshl_add_u64 v[144:145], v[148:149], 2, s[8:9]
	global_load_dword v164, v[144:145], off
	v_lshl_or_b32 v146, s3, 8, v154
	v_ashrrev_i32_e32 v147, 31, v146
	v_lshlrev_b64 v[150:151], 1, v[146:147]
	v_lshlrev_b64 v[162:163], 14, v[148:149]
	v_or_b32_e32 v160, 16, v148
	v_ashrrev_i32_e32 v161, 31, v160
	s_waitcnt vmcnt(0)
	v_fmamk_f32 v146, v164, 0x3a000000, v159
	v_mul_f32_e32 v147, 0x4b800000, v146
	v_cmp_gt_f32_e32 vcc, s56, v146
	s_nop 1
	v_cndmask_b32_e32 v146, v146, v147, vcc
	v_rsq_f32_e32 v149, v146
	v_lshl_add_u64 v[146:147], s[6:7], 0, v[162:163]
	v_lshl_add_u64 v[146:147], v[146:147], 0, v[150:151]
	v_lshl_add_u64 v[162:163], v[160:161], 2, s[8:9]
	v_mul_f32_e32 v164, 0x45800000, v149
	v_cndmask_b32_e32 v164, v149, v164, vcc
	v_pk_mul_f32 v[126:127], v[126:127], v[164:165] op_sel_hi:[1,0]
	v_pk_mul_f32 v[124:125], v[124:125], v[164:165] op_sel_hi:[1,0]
	v_pk_mul_f32 v[122:123], v[122:123], v[164:165] op_sel_hi:[1,0]
	v_pk_mul_f32 v[120:121], v[120:121], v[164:165] op_sel_hi:[1,0]
	v_pk_mul_f32 v[114:115], v[114:115], v[164:165] op_sel_hi:[1,0]
	v_pk_mul_f32 v[112:113], v[112:113], v[164:165] op_sel_hi:[1,0]
	v_pk_mul_f32 v[118:119], v[118:119], v[164:165] op_sel_hi:[1,0]
	v_pk_mul_f32 v[116:117], v[116:117], v[164:165] op_sel_hi:[1,0]
	v_max_f32_e32 v124, 0, v124
	v_max_f32_e32 v120, 0, v120
	v_max_f32_e32 v125, 0, v125
	v_max_f32_e32 v121, 0, v121
	v_max_f32_e32 v126, 0, v126
	v_max_f32_e32 v122, 0, v122
	v_max_f32_e32 v127, 0, v127
	v_max_f32_e32 v123, 0, v123
	v_max_f32_e32 v112, 0, v112
	v_max_f32_e32 v113, 0, v113
	v_max_f32_e32 v114, 0, v114
	v_max_f32_e32 v115, 0, v115
	v_max_f32_e32 v116, 0, v116
	v_max_f32_e32 v117, 0, v117
	v_max_f32_e32 v118, 0, v118
	v_max_f32_e32 v119, 0, v119
	v_mul_f32_e32 v124, v124, v124
	v_mul_f32_e32 v120, v120, v120
	v_mul_f32_e32 v125, v125, v125
	v_mul_f32_e32 v121, v121, v121
	v_mul_f32_e32 v126, v126, v126
	v_mul_f32_e32 v122, v122, v122
	v_mul_f32_e32 v127, v127, v127
	v_mul_f32_e32 v123, v123, v123
	v_mul_f32_e32 v149, v112, v112
	v_mul_f32_e32 v164, v113, v113
	v_mul_f32_e32 v165, v114, v114
	v_mul_f32_e32 v166, v115, v115
	v_cvt_pk_bf16_f32 v112, v124, v125
	v_cvt_pk_bf16_f32 v113, v126, v127
	v_cvt_pk_bf16_f32 v114, v120, v121
	v_cvt_pk_bf16_f32 v115, v122, v123
	v_mul_f32_e32 v116, v116, v116
	v_mul_f32_e32 v117, v117, v117
	v_mul_f32_e32 v118, v118, v118
	v_mul_f32_e32 v119, v119, v119
	global_store_dwordx4 v[146:147], v[112:115], off sc0 sc1 nt
	s_nop 1
	v_cvt_pk_bf16_f32 v112, v116, v117
	v_cvt_pk_bf16_f32 v113, v118, v119
	v_cvt_pk_bf16_f32 v114, v149, v164
	v_cvt_pk_bf16_f32 v115, v165, v166
	global_store_dwordx4 v[146:147], v[112:115], off offset:256 sc0 sc1 nt
	global_load_dword v116, v[162:163], off
	s_waitcnt vmcnt(0)
	v_fmamk_f32 v116, v116, 0x3a000000, v159
	v_mul_f32_e32 v117, 0x4b800000, v116
	v_cmp_gt_f32_e32 vcc, s56, v116
	v_lshlrev_b64 v[114:115], 14, v[160:161]
	v_or_b32_e32 v112, 32, v148
	v_cndmask_b32_e32 v116, v116, v117, vcc
	v_rsq_f32_e32 v118, v116
	v_lshl_add_u64 v[114:115], s[6:7], 0, v[114:115]
	v_ashrrev_i32_e32 v113, 31, v112
	v_lshl_add_u64 v[114:115], v[114:115], 0, v[150:151]
	v_mul_f32_e32 v119, 0x45800000, v118
	v_cndmask_b32_e32 v118, v118, v119, vcc
	v_pk_mul_f32 v[110:111], v[110:111], v[118:119] op_sel_hi:[1,0]
	v_pk_mul_f32 v[108:109], v[108:109], v[118:119] op_sel_hi:[1,0]
	v_pk_mul_f32 v[106:107], v[106:107], v[118:119] op_sel_hi:[1,0]
	v_pk_mul_f32 v[104:105], v[104:105], v[118:119] op_sel_hi:[1,0]
	v_pk_mul_f32 v[98:99], v[98:99], v[118:119] op_sel_hi:[1,0]
	v_pk_mul_f32 v[96:97], v[96:97], v[118:119] op_sel_hi:[1,0]
	v_pk_mul_f32 v[102:103], v[102:103], v[118:119] op_sel_hi:[1,0]
	v_pk_mul_f32 v[100:101], v[100:101], v[118:119] op_sel_hi:[1,0]
	v_max_f32_e32 v108, 0, v108
	v_max_f32_e32 v104, 0, v104
	v_max_f32_e32 v109, 0, v109
	v_max_f32_e32 v105, 0, v105
	v_max_f32_e32 v110, 0, v110
	v_max_f32_e32 v106, 0, v106
	v_max_f32_e32 v111, 0, v111
	v_max_f32_e32 v107, 0, v107
	v_max_f32_e32 v96, 0, v96
	v_max_f32_e32 v97, 0, v97
	v_max_f32_e32 v98, 0, v98
	v_max_f32_e32 v99, 0, v99
	v_max_f32_e32 v100, 0, v100
	v_max_f32_e32 v101, 0, v101
	v_max_f32_e32 v102, 0, v102
	v_max_f32_e32 v103, 0, v103
	v_mul_f32_e32 v108, v108, v108
	v_mul_f32_e32 v104, v104, v104
	v_mul_f32_e32 v109, v109, v109
	v_mul_f32_e32 v105, v105, v105
	v_mul_f32_e32 v110, v110, v110
	v_mul_f32_e32 v106, v106, v106
	v_mul_f32_e32 v111, v111, v111
	v_mul_f32_e32 v107, v107, v107
	v_mul_f32_e32 v118, v96, v96
	v_mul_f32_e32 v119, v97, v97
	v_mul_f32_e32 v120, v98, v98
	v_mul_f32_e32 v121, v99, v99
	v_cvt_pk_bf16_f32 v96, v108, v109
	v_cvt_pk_bf16_f32 v97, v110, v111
	v_cvt_pk_bf16_f32 v98, v104, v105
	v_cvt_pk_bf16_f32 v99, v106, v107
	v_lshl_add_u64 v[116:117], v[112:113], 2, s[8:9]
	v_mul_f32_e32 v100, v100, v100
	v_mul_f32_e32 v101, v101, v101
	v_mul_f32_e32 v102, v102, v102
	v_mul_f32_e32 v103, v103, v103
	global_store_dwordx4 v[114:115], v[96:99], off sc0 sc1 nt
	s_nop 1
	v_cvt_pk_bf16_f32 v96, v100, v101
	v_cvt_pk_bf16_f32 v97, v102, v103
	v_cvt_pk_bf16_f32 v98, v118, v119
	v_cvt_pk_bf16_f32 v99, v120, v121
	global_store_dwordx4 v[114:115], v[96:99], off offset:256 sc0 sc1 nt
	global_load_dword v100, v[116:117], off
	s_waitcnt vmcnt(0)
	v_fmamk_f32 v100, v100, 0x3a000000, v159
	v_mul_f32_e32 v101, 0x4b800000, v100
	v_cmp_gt_f32_e32 vcc, s56, v100
	v_lshlrev_b64 v[98:99], 14, v[112:113]
	v_or_b32_e32 v96, 48, v148
	v_cndmask_b32_e32 v100, v100, v101, vcc
	v_rsq_f32_e32 v102, v100
	v_lshl_add_u64 v[98:99], s[6:7], 0, v[98:99]
	v_ashrrev_i32_e32 v97, 31, v96
	v_lshl_add_u64 v[98:99], v[98:99], 0, v[150:151]
	v_mul_f32_e32 v103, 0x45800000, v102
	v_cndmask_b32_e32 v102, v102, v103, vcc
	v_pk_mul_f32 v[94:95], v[94:95], v[102:103] op_sel_hi:[1,0]
	v_pk_mul_f32 v[92:93], v[92:93], v[102:103] op_sel_hi:[1,0]
	v_pk_mul_f32 v[90:91], v[90:91], v[102:103] op_sel_hi:[1,0]
	v_pk_mul_f32 v[88:89], v[88:89], v[102:103] op_sel_hi:[1,0]
	v_pk_mul_f32 v[82:83], v[82:83], v[102:103] op_sel_hi:[1,0]
	v_pk_mul_f32 v[80:81], v[80:81], v[102:103] op_sel_hi:[1,0]
	v_pk_mul_f32 v[86:87], v[86:87], v[102:103] op_sel_hi:[1,0]
	v_pk_mul_f32 v[84:85], v[84:85], v[102:103] op_sel_hi:[1,0]
	v_max_f32_e32 v92, 0, v92
	v_max_f32_e32 v88, 0, v88
	v_max_f32_e32 v93, 0, v93
	v_max_f32_e32 v89, 0, v89
	v_max_f32_e32 v94, 0, v94
	v_max_f32_e32 v90, 0, v90
	v_max_f32_e32 v95, 0, v95
	v_max_f32_e32 v91, 0, v91
	v_max_f32_e32 v80, 0, v80
	v_max_f32_e32 v81, 0, v81
	v_max_f32_e32 v82, 0, v82
	v_max_f32_e32 v83, 0, v83
	v_max_f32_e32 v84, 0, v84
	v_max_f32_e32 v85, 0, v85
	v_max_f32_e32 v86, 0, v86
	v_max_f32_e32 v87, 0, v87
	v_mul_f32_e32 v92, v92, v92
	v_mul_f32_e32 v88, v88, v88
	v_mul_f32_e32 v93, v93, v93
	v_mul_f32_e32 v89, v89, v89
	v_mul_f32_e32 v94, v94, v94
	v_mul_f32_e32 v90, v90, v90
	v_mul_f32_e32 v95, v95, v95
	v_mul_f32_e32 v91, v91, v91
	v_mul_f32_e32 v102, v80, v80
	v_mul_f32_e32 v103, v81, v81
	v_mul_f32_e32 v104, v82, v82
	v_mul_f32_e32 v105, v83, v83
	v_cvt_pk_bf16_f32 v80, v92, v93
	v_cvt_pk_bf16_f32 v81, v94, v95
	v_cvt_pk_bf16_f32 v82, v88, v89
	v_cvt_pk_bf16_f32 v83, v90, v91
	v_lshl_add_u64 v[100:101], v[96:97], 2, s[8:9]
	v_mul_f32_e32 v84, v84, v84
	v_mul_f32_e32 v85, v85, v85
	v_mul_f32_e32 v86, v86, v86
	v_mul_f32_e32 v87, v87, v87
	global_store_dwordx4 v[98:99], v[80:83], off sc0 sc1 nt
	s_nop 1
	v_cvt_pk_bf16_f32 v80, v84, v85
	v_cvt_pk_bf16_f32 v81, v86, v87
	v_cvt_pk_bf16_f32 v82, v102, v103
	v_cvt_pk_bf16_f32 v83, v104, v105
	global_store_dwordx4 v[98:99], v[80:83], off offset:256 sc0 sc1 nt
	global_load_dword v80, v[100:101], off
	s_waitcnt vmcnt(0)
	v_fmamk_f32 v80, v80, 0x3a000000, v159
	v_mul_f32_e32 v81, 0x4b800000, v80
	v_cmp_gt_f32_e32 vcc, s56, v80
	s_nop 1
	v_cndmask_b32_e32 v80, v80, v81, vcc
	v_rsq_f32_e32 v82, v80
	v_lshlrev_b64 v[80:81], 14, v[96:97]
	v_lshl_add_u64 v[80:81], s[6:7], 0, v[80:81]
	v_lshl_add_u64 v[80:81], v[80:81], 0, v[150:151]
	v_mul_f32_e32 v83, 0x45800000, v82
	v_cndmask_b32_e32 v82, v82, v83, vcc
	v_pk_mul_f32 v[78:79], v[78:79], v[82:83] op_sel_hi:[1,0]
	v_pk_mul_f32 v[76:77], v[76:77], v[82:83] op_sel_hi:[1,0]
	v_pk_mul_f32 v[74:75], v[74:75], v[82:83] op_sel_hi:[1,0]
	v_pk_mul_f32 v[72:73], v[72:73], v[82:83] op_sel_hi:[1,0]
	v_pk_mul_f32 v[66:67], v[66:67], v[82:83] op_sel_hi:[1,0]
	v_pk_mul_f32 v[64:65], v[64:65], v[82:83] op_sel_hi:[1,0]
	v_pk_mul_f32 v[70:71], v[70:71], v[82:83] op_sel_hi:[1,0]
	v_pk_mul_f32 v[68:69], v[68:69], v[82:83] op_sel_hi:[1,0]
	v_max_f32_e32 v76, 0, v76
	v_max_f32_e32 v72, 0, v72
	v_max_f32_e32 v77, 0, v77
	v_max_f32_e32 v73, 0, v73
	v_max_f32_e32 v78, 0, v78
	v_max_f32_e32 v74, 0, v74
	v_max_f32_e32 v79, 0, v79
	v_max_f32_e32 v75, 0, v75
	v_max_f32_e32 v64, 0, v64
	v_max_f32_e32 v65, 0, v65
	v_max_f32_e32 v66, 0, v66
	v_max_f32_e32 v67, 0, v67
	v_max_f32_e32 v68, 0, v68
	v_max_f32_e32 v69, 0, v69
	v_max_f32_e32 v70, 0, v70
	v_max_f32_e32 v71, 0, v71
	v_mul_f32_e32 v76, v76, v76
	v_mul_f32_e32 v72, v72, v72
	v_mul_f32_e32 v77, v77, v77
	v_mul_f32_e32 v73, v73, v73
	v_mul_f32_e32 v78, v78, v78
	v_mul_f32_e32 v74, v74, v74
	v_mul_f32_e32 v79, v79, v79
	v_mul_f32_e32 v75, v75, v75
	v_mul_f32_e32 v82, v64, v64
	v_mul_f32_e32 v83, v65, v65
	v_mul_f32_e32 v84, v66, v66
	v_mul_f32_e32 v85, v67, v67
	v_cvt_pk_bf16_f32 v64, v76, v77
	v_cvt_pk_bf16_f32 v65, v78, v79
	v_cvt_pk_bf16_f32 v66, v72, v73
	v_cvt_pk_bf16_f32 v67, v74, v75
	v_mul_f32_e32 v68, v68, v68
	v_mul_f32_e32 v69, v69, v69
	v_mul_f32_e32 v70, v70, v70
	v_mul_f32_e32 v71, v71, v71
	global_store_dwordx4 v[80:81], v[64:67], off sc0 sc1 nt
	s_nop 1
	v_cvt_pk_bf16_f32 v64, v68, v69
	v_cvt_pk_bf16_f32 v65, v70, v71
	v_cvt_pk_bf16_f32 v66, v82, v83
	v_cvt_pk_bf16_f32 v67, v84, v85
	global_store_dwordx4 v[80:81], v[64:67], off offset:256 sc0 sc1 nt
	global_load_dword v66, v[144:145], off offset:512
	s_nop 0
	v_lshl_add_u64 v[64:65], v[146:147], 0, s[14:15]
	s_waitcnt vmcnt(0)
	v_fmamk_f32 v66, v66, 0x3a000000, v159
	v_mul_f32_e32 v67, 0x4b800000, v66
	v_cmp_gt_f32_e32 vcc, s56, v66
	s_nop 1
	v_cndmask_b32_e32 v66, v66, v67, vcc
	v_rsq_f32_e32 v68, v66
	v_add_co_u32_e64 v66, s[2:3], s57, v146
	v_mul_f32_e32 v69, 0x45800000, v68
	v_cndmask_b32_e32 v68, v68, v69, vcc
	v_pk_mul_f32 v[62:63], v[62:63], v[68:69] op_sel_hi:[1,0]
	v_pk_mul_f32 v[60:61], v[60:61], v[68:69] op_sel_hi:[1,0]
	v_pk_mul_f32 v[58:59], v[58:59], v[68:69] op_sel_hi:[1,0]
	v_pk_mul_f32 v[56:57], v[56:57], v[68:69] op_sel_hi:[1,0]
	v_pk_mul_f32 v[50:51], v[50:51], v[68:69] op_sel_hi:[1,0]
	v_pk_mul_f32 v[48:49], v[48:49], v[68:69] op_sel_hi:[1,0]
	v_pk_mul_f32 v[54:55], v[54:55], v[68:69] op_sel_hi:[1,0]
	v_pk_mul_f32 v[52:53], v[52:53], v[68:69] op_sel_hi:[1,0]
	v_max_f32_e32 v60, 0, v60
	v_max_f32_e32 v56, 0, v56
	v_max_f32_e32 v61, 0, v61
	v_max_f32_e32 v57, 0, v57
	v_max_f32_e32 v62, 0, v62
	v_max_f32_e32 v58, 0, v58
	v_max_f32_e32 v63, 0, v63
	v_max_f32_e32 v59, 0, v59
	v_max_f32_e32 v48, 0, v48
	v_max_f32_e32 v49, 0, v49
	v_max_f32_e32 v50, 0, v50
	v_max_f32_e32 v51, 0, v51
	v_addc_co_u32_e64 v67, s[2:3], 0, v147, s[2:3]
	v_max_f32_e32 v52, 0, v52
	v_max_f32_e32 v53, 0, v53
	v_max_f32_e32 v54, 0, v54
	v_max_f32_e32 v55, 0, v55
	v_mul_f32_e32 v60, v60, v60
	v_mul_f32_e32 v56, v56, v56
	v_mul_f32_e32 v61, v61, v61
	v_mul_f32_e32 v57, v57, v57
	v_mul_f32_e32 v62, v62, v62
	v_mul_f32_e32 v58, v58, v58
	v_mul_f32_e32 v63, v63, v63
	v_mul_f32_e32 v59, v59, v59
	v_mul_f32_e32 v68, v48, v48
	v_mul_f32_e32 v69, v49, v49
	v_mul_f32_e32 v70, v50, v50
	v_mul_f32_e32 v71, v51, v51
	v_cvt_pk_bf16_f32 v48, v60, v61
	v_cvt_pk_bf16_f32 v49, v62, v63
	v_cvt_pk_bf16_f32 v50, v56, v57
	v_cvt_pk_bf16_f32 v51, v58, v59
	v_mul_f32_e32 v52, v52, v52
	v_mul_f32_e32 v53, v53, v53
	v_mul_f32_e32 v54, v54, v54
	v_mul_f32_e32 v55, v55, v55
	global_store_dwordx4 v[66:67], v[48:51], off sc0 sc1 nt
	s_nop 1
	v_cvt_pk_bf16_f32 v48, v52, v53
	v_cvt_pk_bf16_f32 v49, v54, v55
	v_cvt_pk_bf16_f32 v50, v68, v69
	v_cvt_pk_bf16_f32 v51, v70, v71
	global_store_dwordx4 v[64:65], v[48:51], off offset:256 sc0 sc1 nt
	global_load_dword v50, v[144:145], off offset:576
	s_nop 0
	v_lshl_add_u64 v[48:49], v[146:147], 0, s[16:17]
	s_waitcnt vmcnt(0)
	v_fmamk_f32 v50, v50, 0x3a000000, v159
	v_mul_f32_e32 v51, 0x4b800000, v50
	v_cmp_gt_f32_e32 vcc, s56, v50
	s_nop 1
	v_cndmask_b32_e32 v50, v50, v51, vcc
	v_rsq_f32_e32 v52, v50
	v_add_co_u32_e64 v50, s[2:3], s58, v146
	v_mul_f32_e32 v53, 0x45800000, v52
	v_cndmask_b32_e32 v52, v52, v53, vcc
	v_pk_mul_f32 v[46:47], v[46:47], v[52:53] op_sel_hi:[1,0]
	v_pk_mul_f32 v[44:45], v[44:45], v[52:53] op_sel_hi:[1,0]
	v_pk_mul_f32 v[42:43], v[42:43], v[52:53] op_sel_hi:[1,0]
	v_pk_mul_f32 v[40:41], v[40:41], v[52:53] op_sel_hi:[1,0]
	v_pk_mul_f32 v[34:35], v[34:35], v[52:53] op_sel_hi:[1,0]
	v_pk_mul_f32 v[32:33], v[32:33], v[52:53] op_sel_hi:[1,0]
	v_pk_mul_f32 v[38:39], v[38:39], v[52:53] op_sel_hi:[1,0]
	v_pk_mul_f32 v[36:37], v[36:37], v[52:53] op_sel_hi:[1,0]
	v_max_f32_e32 v44, 0, v44
	v_max_f32_e32 v40, 0, v40
	v_max_f32_e32 v45, 0, v45
	v_max_f32_e32 v41, 0, v41
	v_max_f32_e32 v46, 0, v46
	v_max_f32_e32 v42, 0, v42
	v_max_f32_e32 v47, 0, v47
	v_max_f32_e32 v43, 0, v43
	v_max_f32_e32 v32, 0, v32
	v_max_f32_e32 v33, 0, v33
	v_max_f32_e32 v34, 0, v34
	v_max_f32_e32 v35, 0, v35
	v_addc_co_u32_e64 v51, s[2:3], 0, v147, s[2:3]
	v_max_f32_e32 v36, 0, v36
	v_max_f32_e32 v37, 0, v37
	v_max_f32_e32 v38, 0, v38
	v_max_f32_e32 v39, 0, v39
	v_mul_f32_e32 v44, v44, v44
	v_mul_f32_e32 v40, v40, v40
	v_mul_f32_e32 v45, v45, v45
	v_mul_f32_e32 v41, v41, v41
	v_mul_f32_e32 v46, v46, v46
	v_mul_f32_e32 v42, v42, v42
	v_mul_f32_e32 v47, v47, v47
	v_mul_f32_e32 v43, v43, v43
	v_mul_f32_e32 v52, v32, v32
	v_mul_f32_e32 v53, v33, v33
	v_mul_f32_e32 v54, v34, v34
	v_mul_f32_e32 v55, v35, v35
	v_cvt_pk_bf16_f32 v32, v44, v45
	v_cvt_pk_bf16_f32 v33, v46, v47
	v_cvt_pk_bf16_f32 v34, v40, v41
	v_cvt_pk_bf16_f32 v35, v42, v43
	v_mul_f32_e32 v36, v36, v36
	v_mul_f32_e32 v37, v37, v37
	v_mul_f32_e32 v38, v38, v38
	v_mul_f32_e32 v39, v39, v39
	global_store_dwordx4 v[50:51], v[32:35], off sc0 sc1 nt
	s_nop 1
	v_cvt_pk_bf16_f32 v32, v36, v37
	v_cvt_pk_bf16_f32 v33, v38, v39
	v_cvt_pk_bf16_f32 v34, v52, v53
	v_cvt_pk_bf16_f32 v35, v54, v55
	global_store_dwordx4 v[48:49], v[32:35], off offset:256 sc0 sc1 nt
	global_load_dword v34, v[144:145], off offset:640
	s_nop 0
	v_lshl_add_u64 v[32:33], v[146:147], 0, s[18:19]
	s_waitcnt vmcnt(0)
	v_fmamk_f32 v34, v34, 0x3a000000, v159
	v_mul_f32_e32 v35, 0x4b800000, v34
	v_cmp_gt_f32_e32 vcc, s56, v34
	s_nop 1
	v_cndmask_b32_e32 v34, v34, v35, vcc
	v_rsq_f32_e32 v36, v34
	v_add_co_u32_e64 v34, s[2:3], s59, v146
	v_mul_f32_e32 v37, 0x45800000, v36
	v_cndmask_b32_e32 v36, v36, v37, vcc
	v_pk_mul_f32 v[30:31], v[30:31], v[36:37] op_sel_hi:[1,0]
	v_pk_mul_f32 v[28:29], v[28:29], v[36:37] op_sel_hi:[1,0]
	v_pk_mul_f32 v[26:27], v[26:27], v[36:37] op_sel_hi:[1,0]
	v_pk_mul_f32 v[24:25], v[24:25], v[36:37] op_sel_hi:[1,0]
	v_pk_mul_f32 v[18:19], v[18:19], v[36:37] op_sel_hi:[1,0]
	v_pk_mul_f32 v[16:17], v[16:17], v[36:37] op_sel_hi:[1,0]
	v_pk_mul_f32 v[22:23], v[22:23], v[36:37] op_sel_hi:[1,0]
	v_pk_mul_f32 v[20:21], v[20:21], v[36:37] op_sel_hi:[1,0]
	v_max_f32_e32 v28, 0, v28
	v_max_f32_e32 v24, 0, v24
	v_max_f32_e32 v29, 0, v29
	v_max_f32_e32 v25, 0, v25
	v_max_f32_e32 v30, 0, v30
	v_max_f32_e32 v26, 0, v26
	v_max_f32_e32 v31, 0, v31
	v_max_f32_e32 v27, 0, v27
	v_max_f32_e32 v16, 0, v16
	v_max_f32_e32 v17, 0, v17
	v_max_f32_e32 v18, 0, v18
	v_max_f32_e32 v19, 0, v19
	v_addc_co_u32_e64 v35, s[2:3], 0, v147, s[2:3]
	v_max_f32_e32 v20, 0, v20
	v_max_f32_e32 v21, 0, v21
	v_max_f32_e32 v22, 0, v22
	v_max_f32_e32 v23, 0, v23
	v_mul_f32_e32 v28, v28, v28
	v_mul_f32_e32 v24, v24, v24
	v_mul_f32_e32 v29, v29, v29
	v_mul_f32_e32 v25, v25, v25
	v_mul_f32_e32 v30, v30, v30
	v_mul_f32_e32 v26, v26, v26
	v_mul_f32_e32 v31, v31, v31
	v_mul_f32_e32 v27, v27, v27
	v_mul_f32_e32 v36, v16, v16
	v_mul_f32_e32 v37, v17, v17
	v_mul_f32_e32 v38, v18, v18
	v_mul_f32_e32 v39, v19, v19
	v_cvt_pk_bf16_f32 v16, v28, v29
	v_cvt_pk_bf16_f32 v17, v30, v31
	v_cvt_pk_bf16_f32 v18, v24, v25
	v_cvt_pk_bf16_f32 v19, v26, v27
	v_mul_f32_e32 v20, v20, v20
	v_mul_f32_e32 v21, v21, v21
	v_mul_f32_e32 v22, v22, v22
	v_mul_f32_e32 v23, v23, v23
	global_store_dwordx4 v[34:35], v[16:19], off sc0 sc1 nt
	s_andn2_b64 vcc, exec, s[0:1]
	s_nop 0
	v_cvt_pk_bf16_f32 v16, v20, v21
	v_cvt_pk_bf16_f32 v17, v22, v23
	v_cvt_pk_bf16_f32 v18, v36, v37
	v_cvt_pk_bf16_f32 v19, v38, v39
	global_store_dwordx4 v[32:33], v[16:19], off offset:256 sc0 sc1 nt
	global_load_dword v18, v[144:145], off offset:704
	s_nop 0
	v_lshl_add_u64 v[16:17], v[146:147], 0, s[20:21]
	s_waitcnt vmcnt(0)
	v_fmamk_f32 v18, v18, 0x3a000000, v159
	v_mul_f32_e32 v19, 0x4b800000, v18
	v_cmp_gt_f32_e64 s[0:1], s56, v18
	s_nop 1
	v_cndmask_b32_e64 v18, v18, v19, s[0:1]
	v_rsq_f32_e32 v20, v18
	v_add_co_u32_e64 v18, s[2:3], s60, v146
	v_mul_f32_e32 v21, 0x45800000, v20
	v_cndmask_b32_e64 v20, v20, v21, s[0:1]
	v_pk_mul_f32 v[14:15], v[14:15], v[20:21] op_sel_hi:[1,0]
	v_pk_mul_f32 v[12:13], v[12:13], v[20:21] op_sel_hi:[1,0]
	v_pk_mul_f32 v[10:11], v[10:11], v[20:21] op_sel_hi:[1,0]
	v_pk_mul_f32 v[8:9], v[8:9], v[20:21] op_sel_hi:[1,0]
	v_pk_mul_f32 v[2:3], v[2:3], v[20:21] op_sel_hi:[1,0]
	v_pk_mul_f32 v[0:1], v[0:1], v[20:21] op_sel_hi:[1,0]
	v_pk_mul_f32 v[6:7], v[6:7], v[20:21] op_sel_hi:[1,0]
	v_pk_mul_f32 v[4:5], v[4:5], v[20:21] op_sel_hi:[1,0]
	v_max_f32_e32 v12, 0, v12
	v_max_f32_e32 v8, 0, v8
	v_max_f32_e32 v13, 0, v13
	v_max_f32_e32 v9, 0, v9
	v_max_f32_e32 v14, 0, v14
	v_max_f32_e32 v10, 0, v10
	v_max_f32_e32 v15, 0, v15
	v_max_f32_e32 v11, 0, v11
	v_max_f32_e32 v0, 0, v0
	v_max_f32_e32 v1, 0, v1
	v_max_f32_e32 v2, 0, v2
	v_max_f32_e32 v3, 0, v3
	v_addc_co_u32_e64 v19, s[2:3], 0, v147, s[2:3]
	v_max_f32_e32 v4, 0, v4
	v_max_f32_e32 v5, 0, v5
	v_max_f32_e32 v6, 0, v6
	v_max_f32_e32 v7, 0, v7
	v_mul_f32_e32 v12, v12, v12
	v_mul_f32_e32 v8, v8, v8
	v_mul_f32_e32 v13, v13, v13
	v_mul_f32_e32 v9, v9, v9
	v_mul_f32_e32 v14, v14, v14
	v_mul_f32_e32 v10, v10, v10
	v_mul_f32_e32 v15, v15, v15
	v_mul_f32_e32 v11, v11, v11
	v_mul_f32_e32 v20, v0, v0
	v_mul_f32_e32 v21, v1, v1
	v_mul_f32_e32 v22, v2, v2
	v_mul_f32_e32 v23, v3, v3
	v_cvt_pk_bf16_f32 v0, v12, v13
	v_cvt_pk_bf16_f32 v1, v14, v15
	v_cvt_pk_bf16_f32 v2, v8, v9
	v_cvt_pk_bf16_f32 v3, v10, v11
	s_mov_b64 s[0:1], -1
	v_mul_f32_e32 v4, v4, v4
	v_mul_f32_e32 v5, v5, v5
	v_mul_f32_e32 v6, v6, v6
	v_mul_f32_e32 v7, v7, v7
	global_store_dwordx4 v[18:19], v[0:3], off sc0 sc1 nt
	s_nop 1
	v_cvt_pk_bf16_f32 v0, v4, v5
	v_cvt_pk_bf16_f32 v1, v6, v7
	v_cvt_pk_bf16_f32 v2, v20, v21
	v_cvt_pk_bf16_f32 v3, v22, v23
	global_store_dwordx4 v[16:17], v[0:3], off offset:256 sc0 sc1 nt
	s_cbranch_vccnz .LBB0_1418
	s_andn2_b64 vcc, exec, s[4:5]
	s_cbranch_vccnz .LBB0_1417
	s_barrier
	s_branch .LBB0_1417
